# attention tile head holds only the first K fragment reads: all eight LDS-DMA pieces are issued between the QK MFMAs (none before the first MFMA)
# speedup vs baseline: 1.0061x; 1.0026x over previous
.Lat_loop:
	s_waitcnt vmcnt(0) lgkmcnt(0)
	s_barrier
	s_cmp_gt_u32 s58, s89
	s_cbranch_scc1 .Lat_inactive0
	ds_read_b128 v[162:165], v234
	ds_read_b128 v[166:169], v235
	ds_read_b128 v[170:173], v236
	ds_read_b128 v[174:177], v237
	s_waitcnt lgkmcnt(2)
	v_mfma_f32_16x16x32_bf16 v[130:133], v[162:165], v[178:181], v[246:249]
	s_add_i32 m0, s71, 0x0
	v_mfma_f32_16x16x32_bf16 v[146:149], v[162:165], v[194:197], v[250:253]
	ds_read_b128 v[162:165], v234 offset:4096
	global_load_lds_dwordx4 v231, s[50:51]
	v_mfma_f32_16x16x32_bf16 v[130:133], v[166:169], v[182:185], v[130:133]
	v_mfma_f32_16x16x32_bf16 v[146:149], v[166:169], v[198:201], v[146:149]
	ds_read_b128 v[166:169], v235 offset:4096
	s_waitcnt lgkmcnt(2)
	v_mfma_f32_16x16x32_bf16 v[130:133], v[170:173], v[186:189], v[130:133]
	s_add_i32 m0, s71, 0x400
	v_mfma_f32_16x16x32_bf16 v[146:149], v[170:173], v[202:205], v[146:149]
	ds_read_b128 v[170:173], v236 offset:4096
	global_load_lds_dwordx4 v229, s[50:51]
	v_mfma_f32_16x16x32_bf16 v[130:133], v[174:177], v[190:193], v[130:133]
	v_mfma_f32_16x16x32_bf16 v[146:149], v[174:177], v[206:209], v[146:149]
	ds_read_b128 v[174:177], v237 offset:4096
	s_waitcnt lgkmcnt(2)
	v_mfma_f32_16x16x32_bf16 v[134:137], v[162:165], v[178:181], v[246:249]
	s_add_i32 m0, s71, 0x800
	v_mfma_f32_16x16x32_bf16 v[150:153], v[162:165], v[194:197], v[250:253]
	ds_read_b128 v[162:165], v234 offset:8192
	global_load_lds_dwordx4 v227, s[50:51]
	v_mfma_f32_16x16x32_bf16 v[134:137], v[166:169], v[182:185], v[134:137]
	v_mfma_f32_16x16x32_bf16 v[150:153], v[166:169], v[198:201], v[150:153]
	ds_read_b128 v[166:169], v235 offset:8192
	s_waitcnt lgkmcnt(2)
	v_mfma_f32_16x16x32_bf16 v[134:137], v[170:173], v[186:189], v[134:137]
	s_add_i32 m0, s71, 0xc00
	v_mfma_f32_16x16x32_bf16 v[150:153], v[170:173], v[202:205], v[150:153]
	ds_read_b128 v[170:173], v236 offset:8192
	global_load_lds_dwordx4 v225, s[50:51]
	v_mfma_f32_16x16x32_bf16 v[134:137], v[174:177], v[190:193], v[134:137]
	v_mfma_f32_16x16x32_bf16 v[150:153], v[174:177], v[206:209], v[150:153]
	ds_read_b128 v[174:177], v237 offset:8192
	s_waitcnt lgkmcnt(2)
	v_mfma_f32_16x16x32_bf16 v[138:141], v[162:165], v[178:181], v[246:249]
	s_add_i32 m0, s71, 0x1000
	v_mfma_f32_16x16x32_bf16 v[154:157], v[162:165], v[194:197], v[250:253]
	ds_read_b128 v[162:165], v234 offset:12288
	global_load_lds_dwordx4 v230, s[50:51]
	v_mfma_f32_16x16x32_bf16 v[138:141], v[166:169], v[182:185], v[138:141]
	v_mfma_f32_16x16x32_bf16 v[154:157], v[166:169], v[198:201], v[154:157]
	ds_read_b128 v[166:169], v235 offset:12288
	s_waitcnt lgkmcnt(2)
	v_mfma_f32_16x16x32_bf16 v[138:141], v[170:173], v[186:189], v[138:141]
	s_add_i32 m0, s71, 0x1400
	v_mfma_f32_16x16x32_bf16 v[154:157], v[170:173], v[202:205], v[154:157]
	ds_read_b128 v[170:173], v236 offset:12288
	global_load_lds_dwordx4 v228, s[50:51]
	v_mfma_f32_16x16x32_bf16 v[138:141], v[174:177], v[190:193], v[138:141]
	v_mfma_f32_16x16x32_bf16 v[154:157], v[174:177], v[206:209], v[154:157]
	ds_read_b128 v[174:177], v237 offset:12288
	s_waitcnt lgkmcnt(2)
	v_mfma_f32_16x16x32_bf16 v[142:145], v[162:165], v[178:181], v[246:249]
	s_add_i32 m0, s71, 0x1800
	v_mfma_f32_16x16x32_bf16 v[158:161], v[162:165], v[194:197], v[250:253]
	ds_read_b128 v[162:165], v242
	global_load_lds_dwordx4 v226, s[50:51]
	v_mfma_f32_16x16x32_bf16 v[142:145], v[166:169], v[182:185], v[142:145]
	v_mfma_f32_16x16x32_bf16 v[158:161], v[166:169], v[198:201], v[158:161]
	ds_read_b128 v[166:169], v243
	s_waitcnt lgkmcnt(2)
	v_mfma_f32_16x16x32_bf16 v[142:145], v[170:173], v[186:189], v[142:145]
	s_add_i32 m0, s71, 0x1c00
	v_mfma_f32_16x16x32_bf16 v[158:161], v[170:173], v[202:205], v[158:161]
	ds_read_b128 v[170:173], v242 offset:2048
	global_load_lds_dwordx4 v224, s[50:51]
	v_mfma_f32_16x16x32_bf16 v[142:145], v[174:177], v[190:193], v[142:145]
	v_mfma_f32_16x16x32_bf16 v[158:161], v[174:177], v[206:209], v[158:161]
	ds_read_b128 v[174:177], v243 offset:2048

.Lat_end_a:
.Lat_next0:
	s_add_i32 s58, s58, 1
	v_add_u32_e32 v223, 0xffffffc0, v223
	s_addk_i32 s91, 0x40
	s_add_u32 s50, s50, s100
	s_addc_u32 s51, s51, 0
	s_mov_b32 s94, 0
	s_cmp_gt_u32 s58, s88
	s_cbranch_scc1 .Lat_final
	s_waitcnt vmcnt(0) lgkmcnt(0)
	s_barrier
	s_cmp_gt_u32 s58, s89
	s_cbranch_scc1 .Lat_inactive1
	ds_read_b128 v[162:165], v234 offset:32768
	ds_read_b128 v[166:169], v235 offset:32768
	ds_read_b128 v[170:173], v236 offset:32768
	ds_read_b128 v[174:177], v237 offset:32768
	s_waitcnt lgkmcnt(2)
	v_mfma_f32_16x16x32_bf16 v[130:133], v[162:165], v[178:181], v[246:249]
	s_add_i32 m0, s97, 0x0
	v_mfma_f32_16x16x32_bf16 v[146:149], v[162:165], v[194:197], v[250:253]
	ds_read_b128 v[162:165], v234 offset:36864
	global_load_lds_dwordx4 v231, s[50:51]
	v_mfma_f32_16x16x32_bf16 v[130:133], v[166:169], v[182:185], v[130:133]
	v_mfma_f32_16x16x32_bf16 v[146:149], v[166:169], v[198:201], v[146:149]
	ds_read_b128 v[166:169], v235 offset:36864
	s_waitcnt lgkmcnt(2)
	v_mfma_f32_16x16x32_bf16 v[130:133], v[170:173], v[186:189], v[130:133]
	s_add_i32 m0, s97, 0x400
	v_mfma_f32_16x16x32_bf16 v[146:149], v[170:173], v[202:205], v[146:149]
	ds_read_b128 v[170:173], v236 offset:36864
	global_load_lds_dwordx4 v229, s[50:51]
	v_mfma_f32_16x16x32_bf16 v[130:133], v[174:177], v[190:193], v[130:133]
	v_mfma_f32_16x16x32_bf16 v[146:149], v[174:177], v[206:209], v[146:149]
	ds_read_b128 v[174:177], v237 offset:36864
	s_waitcnt lgkmcnt(2)
	v_mfma_f32_16x16x32_bf16 v[134:137], v[162:165], v[178:181], v[246:249]
	s_add_i32 m0, s97, 0x800
	v_mfma_f32_16x16x32_bf16 v[150:153], v[162:165], v[194:197], v[250:253]
	ds_read_b128 v[162:165], v234 offset:40960
	global_load_lds_dwordx4 v227, s[50:51]
	v_mfma_f32_16x16x32_bf16 v[134:137], v[166:169], v[182:185], v[134:137]
	v_mfma_f32_16x16x32_bf16 v[150:153], v[166:169], v[198:201], v[150:153]
	ds_read_b128 v[166:169], v235 offset:40960
	s_waitcnt lgkmcnt(2)
	v_mfma_f32_16x16x32_bf16 v[134:137], v[170:173], v[186:189], v[134:137]
	s_add_i32 m0, s97, 0xc00
	v_mfma_f32_16x16x32_bf16 v[150:153], v[170:173], v[202:205], v[150:153]
	ds_read_b128 v[170:173], v236 offset:40960
	global_load_lds_dwordx4 v225, s[50:51]
	v_mfma_f32_16x16x32_bf16 v[134:137], v[174:177], v[190:193], v[134:137]
	v_mfma_f32_16x16x32_bf16 v[150:153], v[174:177], v[206:209], v[150:153]
	ds_read_b128 v[174:177], v237 offset:40960
	s_waitcnt lgkmcnt(2)
	v_mfma_f32_16x16x32_bf16 v[138:141], v[162:165], v[178:181], v[246:249]
	s_add_i32 m0, s97, 0x1000
	v_mfma_f32_16x16x32_bf16 v[154:157], v[162:165], v[194:197], v[250:253]
	ds_read_b128 v[162:165], v234 offset:45056
	global_load_lds_dwordx4 v230, s[50:51]
	v_mfma_f32_16x16x32_bf16 v[138:141], v[166:169], v[182:185], v[138:141]
	v_mfma_f32_16x16x32_bf16 v[154:157], v[166:169], v[198:201], v[154:157]
	ds_read_b128 v[166:169], v235 offset:45056
	s_waitcnt lgkmcnt(2)
	v_mfma_f32_16x16x32_bf16 v[138:141], v[170:173], v[186:189], v[138:141]
	s_add_i32 m0, s97, 0x1400
	v_mfma_f32_16x16x32_bf16 v[154:157], v[170:173], v[202:205], v[154:157]
	ds_read_b128 v[170:173], v236 offset:45056
	global_load_lds_dwordx4 v228, s[50:51]
	v_mfma_f32_16x16x32_bf16 v[138:141], v[174:177], v[190:193], v[138:141]
	v_mfma_f32_16x16x32_bf16 v[154:157], v[174:177], v[206:209], v[154:157]
	ds_read_b128 v[174:177], v237 offset:45056
	s_waitcnt lgkmcnt(2)
	v_mfma_f32_16x16x32_bf16 v[142:145], v[162:165], v[178:181], v[246:249]
	s_add_i32 m0, s97, 0x1800
	v_mfma_f32_16x16x32_bf16 v[158:161], v[162:165], v[194:197], v[250:253]
	ds_read_b128 v[162:165], v242 offset:32768
	global_load_lds_dwordx4 v226, s[50:51]
	v_mfma_f32_16x16x32_bf16 v[142:145], v[166:169], v[182:185], v[142:145]
	v_mfma_f32_16x16x32_bf16 v[158:161], v[166:169], v[198:201], v[158:161]
	ds_read_b128 v[166:169], v243 offset:32768
	s_waitcnt lgkmcnt(2)
	v_mfma_f32_16x16x32_bf16 v[142:145], v[170:173], v[186:189], v[142:145]
	s_add_i32 m0, s97, 0x1c00
	v_mfma_f32_16x16x32_bf16 v[158:161], v[170:173], v[202:205], v[158:161]
	ds_read_b128 v[170:173], v242 offset:34816
	global_load_lds_dwordx4 v224, s[50:51]
	v_mfma_f32_16x16x32_bf16 v[142:145], v[174:177], v[190:193], v[142:145]
	v_mfma_f32_16x16x32_bf16 v[158:161], v[174:177], v[206:209], v[158:161]
	ds_read_b128 v[174:177], v243 offset:34816
